# v44 plus merged staging vmcnt waits and e32 encodings for two loop-end adds (slot cleanup stack)
# speedup vs baseline: 1.0015x; 1.0015x over previous
.LBB0_437:
	s_add_i32 s14, s33, 2
	s_cmpk_gt_u32 s33, 0xfd
	s_cselect_b64 s[44:45], -1, 0
	s_and_b64 vcc, exec, s[44:45]
	s_cbranch_vccnz .LBB0_439
	s_and_b32 s4, s14, 2
	s_mulk_i32 s4, 0x4800
	v_add_u32_e32 v84, s4, v173
	s_waitcnt vmcnt(0)
	ds_write_b128 v84, v[132:135]
	ds_write_b128 v84, v[136:139] offset:9216

.LBB0_441:
	s_and_b32 s48, s33, 2
	s_add_i32 s4, s33, -1
	s_and_b32 s49, s4, 3
	s_mul_i32 s4, s48, 0x4800
	v_add_u32_e32 v168, s4, v184
	s_cmp_eq_u32 s33, 0
	ds_read_b128 v[164:167], v168 offset:96
	s_cselect_b64 s[6:7], -1, 0
	s_mulk_i32 s49, 0x4800
	s_and_b64 s[4:5], s[6:7], exec
	s_cselect_b32 s4, 0, s49
	v_add_u32_e32 v84, s4, v184
	v_exp_f32_e32 v64, v64
	v_exp_f32_e32 v65, v65
	s_nop 0
	v_add_f32_e32 v113, v65, v64
	v_cvt_pk_bf16_f32 v112, v64, v65
	ds_read_b128 v[186:189], v84 offset:9280
	ds_read_b128 v[190:193], v84 offset:9312
	ds_read_b128 v[194:197], v84 offset:13888
	ds_read_b128 v[198:201], v84 offset:13920
	v_mfma_f32_32x32x16_bf16 v[80:95], v[80:83], v[148:151], 0
	v_exp_f32_e32 v64, v66
	v_exp_f32_e32 v65, v67
	v_add_f32_e32 v66, v64, v113
	v_add_f32_e32 v66, v65, v66
	v_cvt_pk_bf16_f32 v113, v64, v65
	v_mfma_f32_32x32x16_bf16 v[80:95], v[108:111], v[152:155], v[80:95]
	v_exp_f32_e32 v64, v68
	v_exp_f32_e32 v65, v69
	v_add_f32_e32 v66, v64, v66
	v_cvt_pk_bf16_f32 v114, v64, v65
	v_add_f32_e32 v64, v65, v66
	v_mfma_f32_32x32x16_bf16 v[80:95], v[104:107], v[156:159], v[80:95]
	v_exp_f32_e32 v65, v70
	v_exp_f32_e32 v66, v71
	v_add_f32_e32 v64, v65, v64
	v_cvt_pk_bf16_f32 v115, v65, v66
	v_add_f32_e32 v64, v66, v64
	s_waitcnt lgkmcnt(4)
	v_mfma_f32_32x32x16_bf16 v[80:95], v[164:167], v[160:163], v[80:95]
	v_exp_f32_e32 v65, v72
	v_exp_f32_e32 v66, v73
	v_add_f32_e32 v64, v65, v64
	v_cvt_pk_bf16_f32 v104, v65, v66
	v_add_f32_e32 v64, v66, v64
	s_waitcnt lgkmcnt(0)
	v_mfma_f32_32x32x16_bf16 v[16:31], v[186:189], v[96:99], v[16:31]
	v_exp_f32_e32 v65, v74
	v_exp_f32_e32 v66, v75
	v_add_f32_e32 v64, v65, v64
	v_cvt_pk_bf16_f32 v105, v65, v66
	v_add_f32_e32 v64, v66, v64
	v_mfma_f32_32x32x16_bf16 v[16:31], v[190:193], v[100:103], v[16:31]
	v_exp_f32_e32 v65, v76
	v_exp_f32_e32 v66, v77
	v_add_f32_e32 v64, v65, v64
	v_cvt_pk_bf16_f32 v106, v65, v66
	v_add_f32_e32 v64, v66, v64
	v_mfma_f32_32x32x16_bf16 v[0:15], v[194:197], v[96:99], v[0:15]
	v_exp_f32_e32 v65, v78
	v_exp_f32_e32 v66, v79
	v_add_f32_e32 v64, v65, v64
	v_cvt_pk_bf16_f32 v107, v65, v66
	v_add_f32_e32 v185, v66, v64
	v_exp_f32_e32 v68, v80
	v_exp_f32_e32 v69, v81
	s_nop 0
	v_add_f32_e32 v80, v69, v68
	v_cvt_pk_bf16_f32 v96, v68, v69
	v_mfma_f32_32x32x16_bf16 v[0:15], v[198:201], v[100:103], v[0:15]
	ds_read_b128 v[64:67], v168 offset:4608
	ds_read_b128 v[164:167], v168 offset:4640
	ds_read_b128 v[108:111], v168 offset:4672
	v_cmp_nge_f32_e64 s[4:5], s62, v185
	v_cmp_gt_f32_e32 vcc, s75, v185
	s_and_b64 vcc, s[6:7], vcc
	s_or_b64 s[4:5], s[4:5], vcc
	ds_read_b128 v[186:189], v168 offset:4704
	s_waitcnt lgkmcnt(1)
	v_mfma_f32_32x32x16_bf16 v[64:79], v[64:67], v[116:119], 0
	ds_read_b128 v[190:193], v168 offset:9216
	ds_read_b128 v[194:197], v168 offset:9248
	ds_read_b128 v[198:201], v168 offset:13824
	ds_read_b128 v[230:233], v168 offset:13856
	v_exp_f32_e32 v81, v82
	v_exp_f32_e32 v82, v83
	v_add_f32_e32 v80, v81, v80
	v_add_f32_e32 v80, v82, v80
	v_cvt_pk_bf16_f32 v97, v81, v82
	v_mfma_f32_32x32x16_bf16 v[64:79], v[164:167], v[120:123], v[64:79]
	v_exp_f32_e32 v81, v84
	v_exp_f32_e32 v82, v85
	v_add_f32_e32 v80, v81, v80
	v_cvt_pk_bf16_f32 v98, v81, v82
	v_add_f32_e32 v80, v82, v80
	v_mfma_f32_32x32x16_bf16 v[64:79], v[108:111], v[124:127], v[64:79]
	v_exp_f32_e32 v81, v86
	v_exp_f32_e32 v82, v87
	v_add_f32_e32 v80, v81, v80
	v_cvt_pk_bf16_f32 v99, v81, v82
	v_add_f32_e32 v80, v82, v80
	s_waitcnt lgkmcnt(4)
	v_mfma_f32_32x32x16_bf16 v[64:79], v[186:189], v[128:131], v[64:79]
	v_exp_f32_e32 v81, v88
	v_exp_f32_e32 v82, v89
	v_add_f32_e32 v80, v81, v80
	v_cvt_pk_bf16_f32 v100, v81, v82
	v_add_f32_e32 v80, v82, v80
	s_waitcnt lgkmcnt(0)
	v_mfma_f32_32x32x16_bf16 v[48:63], v[190:193], v[112:115], v[48:63]
	v_exp_f32_e32 v81, v90
	v_exp_f32_e32 v82, v91
	v_add_f32_e32 v80, v81, v80
	v_cvt_pk_bf16_f32 v101, v81, v82
	v_add_f32_e32 v80, v82, v80
	v_mfma_f32_32x32x16_bf16 v[48:63], v[194:197], v[104:107], v[48:63]
	v_exp_f32_e32 v81, v92
	v_exp_f32_e32 v82, v93
	v_add_f32_e32 v80, v81, v80
	v_cvt_pk_bf16_f32 v102, v81, v82
	v_add_f32_e32 v80, v82, v80
	v_mfma_f32_32x32x16_bf16 v[32:47], v[198:201], v[112:115], v[32:47]
	v_exp_f32_e32 v81, v94
	v_exp_f32_e32 v82, v95
	v_add_f32_e32 v80, v81, v80
	v_cvt_pk_bf16_f32 v103, v81, v82
	v_add_f32_e32 v164, v82, v80
	v_exp_f32_e32 v64, v64
	v_exp_f32_e32 v65, v65
	s_nop 0
	v_add_f32_e32 v165, v65, v64
	v_cvt_pk_bf16_f32 v186, v64, v65
	v_mfma_f32_32x32x16_bf16 v[32:47], v[230:233], v[104:107], v[32:47]
	ds_read_b128 v[80:83], v168 offset:4608
	ds_read_b128 v[112:115], v168 offset:4640
	ds_read_b128 v[108:111], v168 offset:4672
	v_cmp_nge_f32_e64 s[8:9], s62, v164
	v_cmp_gt_f32_e32 vcc, s75, v164
	s_and_b64 s[6:7], s[6:7], vcc
	s_or_b64 s[6:7], s[6:7], s[8:9]
	ds_read_b128 v[104:107], v168 offset:4704
	s_waitcnt lgkmcnt(1)
	v_mfma_f32_32x32x16_bf16 v[80:95], v[80:83], v[148:151], 0
	ds_read_b128 v[190:193], v168 offset:9216
	ds_read_b128 v[194:197], v168 offset:9248
	ds_read_b128 v[198:201], v168 offset:13824
	ds_read_b128 v[230:233], v168 offset:13856
	v_exp_f32_e32 v64, v66
	v_exp_f32_e32 v65, v67
	v_add_f32_e32 v66, v64, v165
	v_add_f32_e32 v66, v65, v66
	v_cvt_pk_bf16_f32 v187, v64, v65
	v_mfma_f32_32x32x16_bf16 v[80:95], v[112:115], v[152:155], v[80:95]
	v_exp_f32_e32 v64, v68
	v_exp_f32_e32 v65, v69
	v_add_f32_e32 v66, v64, v66
	v_cvt_pk_bf16_f32 v188, v64, v65
	v_add_f32_e32 v64, v65, v66
	v_mfma_f32_32x32x16_bf16 v[80:95], v[108:111], v[156:159], v[80:95]
	v_exp_f32_e32 v65, v70
	v_exp_f32_e32 v66, v71
	v_add_f32_e32 v64, v65, v64
	v_cvt_pk_bf16_f32 v189, v65, v66
	v_add_f32_e32 v64, v66, v64
	s_waitcnt lgkmcnt(4)
	v_mfma_f32_32x32x16_bf16 v[80:95], v[104:107], v[160:163], v[80:95]
	v_exp_f32_e32 v65, v72
	v_exp_f32_e32 v66, v73
	v_add_f32_e32 v64, v65, v64
	v_cvt_pk_bf16_f32 v108, v65, v66
	v_add_f32_e32 v64, v66, v64
	s_waitcnt lgkmcnt(0)
	v_mfma_f32_32x32x16_bf16 v[16:31], v[190:193], v[96:99], v[16:31]
	v_exp_f32_e32 v65, v74
	v_exp_f32_e32 v66, v75
	v_add_f32_e32 v64, v65, v64
	v_cvt_pk_bf16_f32 v109, v65, v66
	v_add_f32_e32 v64, v66, v64
	v_mfma_f32_32x32x16_bf16 v[16:31], v[194:197], v[100:103], v[16:31]
	v_exp_f32_e32 v65, v76
	v_exp_f32_e32 v66, v77
	v_add_f32_e32 v64, v65, v64
	v_cvt_pk_bf16_f32 v110, v65, v66
	v_add_f32_e32 v64, v66, v64
	v_mfma_f32_32x32x16_bf16 v[0:15], v[198:201], v[96:99], v[0:15]
	v_exp_f32_e32 v65, v78
	v_exp_f32_e32 v66, v79
	v_add_f32_e32 v64, v65, v64
	v_cvt_pk_bf16_f32 v111, v65, v66
	v_add_f32_e32 v104, v66, v64
	v_exp_f32_e32 v68, v80
	v_exp_f32_e32 v69, v81
	s_nop 0
	v_add_f32_e32 v81, v69, v68
	v_cvt_pk_bf16_f32 v80, v68, v69
	v_mfma_f32_32x32x16_bf16 v[0:15], v[230:233], v[100:103], v[0:15]
	ds_read_b128 v[64:67], v168 offset:18432
	ds_read_b128 v[96:99], v168 offset:18464
	ds_read_b128 v[112:115], v168 offset:18496
	v_cmp_nge_f32_e64 s[8:9], s62, v104
	ds_read_b128 v[100:103], v168 offset:18528
	s_waitcnt lgkmcnt(1)
	v_mfma_f32_32x32x16_bf16 v[64:79], v[64:67], v[116:119], 0
	ds_read_b128 v[190:193], v168 offset:9280
	ds_read_b128 v[194:197], v168 offset:9312
	ds_read_b128 v[198:201], v168 offset:13888
	ds_read_b128 v[230:233], v168 offset:13920
	v_exp_f32_e32 v82, v82
	v_exp_f32_e32 v83, v83
	v_add_f32_e32 v81, v82, v81
	v_add_f32_e32 v105, v83, v81
	v_cvt_pk_bf16_f32 v81, v82, v83
	v_mfma_f32_32x32x16_bf16 v[64:79], v[96:99], v[120:123], v[64:79]
	v_exp_f32_e32 v82, v84
	v_exp_f32_e32 v83, v85
	v_add_f32_e32 v84, v82, v105
	v_cvt_pk_bf16_f32 v82, v82, v83
	v_add_f32_e32 v83, v83, v84
	v_mfma_f32_32x32x16_bf16 v[64:79], v[112:115], v[124:127], v[64:79]
	v_exp_f32_e32 v84, v86
	v_exp_f32_e32 v85, v87
	v_add_f32_e32 v86, v84, v83
	v_cvt_pk_bf16_f32 v83, v84, v85
	v_add_f32_e32 v84, v85, v86
	s_waitcnt lgkmcnt(4)
	v_mfma_f32_32x32x16_bf16 v[64:79], v[100:103], v[128:131], v[64:79]
	v_exp_f32_e32 v85, v88
	v_exp_f32_e32 v86, v89
	v_add_f32_e32 v87, v85, v84
	v_cvt_pk_bf16_f32 v84, v85, v86
	v_add_f32_e32 v85, v86, v87
	s_waitcnt lgkmcnt(0)
	v_mfma_f32_32x32x16_bf16 v[48:63], v[190:193], v[186:189], v[48:63]
	v_exp_f32_e32 v86, v90
	v_exp_f32_e32 v87, v91
	v_add_f32_e32 v88, v86, v85
	v_cvt_pk_bf16_f32 v85, v86, v87
	v_add_f32_e32 v86, v87, v88
	v_mfma_f32_32x32x16_bf16 v[48:63], v[194:197], v[108:111], v[48:63]
	v_exp_f32_e32 v87, v92
	v_exp_f32_e32 v88, v93
	v_add_f32_e32 v89, v87, v86
	v_cvt_pk_bf16_f32 v86, v87, v88
	v_add_f32_e32 v87, v88, v89
	v_mfma_f32_32x32x16_bf16 v[32:47], v[198:201], v[186:189], v[32:47]
	v_exp_f32_e32 v88, v94
	v_exp_f32_e32 v89, v95
	v_add_f32_e32 v90, v88, v87
	v_cvt_pk_bf16_f32 v87, v88, v89
	v_add_f32_e32 v105, v89, v90
	v_mfma_f32_32x32x16_bf16 v[32:47], v[230:233], v[108:111], v[32:47]
	ds_read_b128 v[96:99], v168 offset:18432
	ds_read_b128 v[92:95], v168 offset:18464
	ds_read_b128 v[88:91], v168 offset:18496
	v_cmp_nge_f32_e64 s[10:11], s62, v105
	s_barrier
	s_waitcnt lgkmcnt(0)
	s_cmpk_gt_u32 s33, 0xfc
	s_cbranch_scc1 .LBB0_447
	v_add_u32_e32 v100, s49, v173
	s_waitcnt vmcnt(0)
	ds_write_b128 v100, v[140:143]
	ds_write_b128 v100, v[144:147] offset:9216

.LBB0_923:
	s_add_i32 s30, s61, 2
	s_cmpk_gt_u32 s61, 0xfd
	s_cselect_b64 s[44:45], -1, 0
	s_and_b64 vcc, exec, s[44:45]
	s_cbranch_vccnz .LBB0_925
	s_and_b32 s6, s30, 2
	s_mulk_i32 s6, 0x5800
	s_add_i32 s6, s6, 0
	v_add_u32_e32 v84, s6, v238
	v_add_u32_e32 v85, s6, v239
	v_add_u32_e32 v86, s6, v240
	s_waitcnt vmcnt(0)
	ds_write_b128 v84, v[142:145]
	ds_write_b64 v85, v[188:189] offset:128
	ds_write_b128 v86, v[146:149] offset:13312

.LBB0_927:
	s_add_i32 s6, s61, -1
	s_and_b32 s77, s61, 2
	s_and_b32 s79, s6, 3
	s_cmp_eq_u32 s61, 0
	s_cselect_b64 s[8:9], -1, 0
	s_mulk_i32 s79, 0x5800
	s_and_b64 s[6:7], s[8:9], exec
	s_mul_i32 s78, s77, 0x5800
	s_cselect_b32 s6, 0, s79
	s_add_i32 s76, s78, 0
	v_add_u32_e32 v199, s76, v241
	v_add_u32_e32 v210, s6, v244
	v_exp_f32_e32 v64, v64
	v_exp_f32_e32 v65, v65
	s_nop 0
	v_add_f32_e32 v84, v65, v64
	v_cvt_pk_bf16_f32 v178, v64, v65
	v_exp_f32_e32 v64, v66
	ds_read_b128 v[182:185], v199 offset:96
	ds_read_b128 v[246:249], v199 offset:128
	ds_read_b128 v[250:253], v199 offset:160
	v_exp_f32_e32 v65, v67
	v_add_f32_e32 v66, v64, v84
	v_mfma_f32_32x32x16_bf16 v[80:95], v[80:83], v[122:125], 0
	v_add_f32_e32 v66, v65, v66
	v_cvt_pk_bf16_f32 v179, v64, v65
	v_mfma_f32_32x32x16_bf16 v[80:95], v[174:177], v[126:129], v[80:95]
	v_exp_f32_e32 v64, v68
	v_exp_f32_e32 v65, v69
	v_add_f32_e32 v66, v64, v66
	v_add_f32_e32 v66, v65, v66
	v_cvt_pk_bf16_f32 v180, v64, v65
	v_mfma_f32_32x32x16_bf16 v[80:95], v[170:173], v[130:133], v[80:95]
	v_exp_f32_e32 v64, v70
	v_exp_f32_e32 v65, v71
	v_add_f32_e32 v66, v64, v66
	v_add_f32_e32 v170, v65, v66
	v_cvt_pk_bf16_f32 v181, v64, v65
	s_waitcnt lgkmcnt(0)
	v_mfma_f32_32x32x16_bf16 v[80:95], v[182:185], v[134:137], v[80:95]
	ds_read_b128 v[64:67], v210 offset:13376
	ds_read_b128 v[68:71], v210 offset:13408
	ds_read_b128 v[174:177], v210 offset:17984
	ds_read_b128 v[218:221], v210 offset:18016
	v_exp_f32_e32 v72, v72
	v_exp_f32_e32 v73, v73
	v_add_f32_e32 v170, v72, v170
	v_add_f32_e32 v171, v73, v170
	v_cvt_pk_bf16_f32 v170, v72, v73
	v_mfma_f32_32x32x16_bf16 v[80:95], v[246:249], v[154:157], v[80:95]
	v_exp_f32_e32 v72, v74
	v_exp_f32_e32 v73, v75
	v_add_f32_e32 v74, v72, v171
	v_add_f32_e32 v74, v73, v74
	v_cvt_pk_bf16_f32 v171, v72, v73
	v_mfma_f32_32x32x16_bf16 v[80:95], v[250:253], v[158:161], v[80:95]
	v_exp_f32_e32 v72, v76
	v_exp_f32_e32 v73, v77
	v_add_f32_e32 v74, v72, v74
	v_add_f32_e32 v74, v73, v74
	v_cvt_pk_bf16_f32 v172, v72, v73
	s_waitcnt lgkmcnt(0)
	v_mfma_f32_32x32x16_bf16 v[16:31], v[64:67], v[162:165], v[16:31]
	v_exp_f32_e32 v64, v78
	v_exp_f32_e32 v65, v79
	v_add_f32_e32 v66, v64, v74
	v_add_f32_e32 v246, v65, v66
	v_cvt_pk_bf16_f32 v173, v64, v65
	v_mfma_f32_32x32x16_bf16 v[0:15], v[174:177], v[162:165], v[0:15]
	ds_read_b128 v[64:67], v199 offset:6656
	ds_read_b128 v[182:185], v199 offset:6688
	ds_read_b128 v[174:177], v199 offset:6720
	v_cmp_nge_f32_e64 s[6:7], s48, v246
	v_cmp_gt_f32_e32 vcc, s49, v246
	v_mfma_f32_32x32x16_bf16 v[16:31], v[68:71], v[166:169], v[16:31]
	v_exp_f32_e32 v68, v80
	v_exp_f32_e32 v69, v81
	s_nop 0
	v_add_f32_e32 v70, v69, v68
	v_cvt_pk_bf16_f32 v162, v68, v69
	v_exp_f32_e32 v80, v82
	v_exp_f32_e32 v81, v83
	v_add_f32_e32 v82, v80, v70
	v_mfma_f32_32x32x16_bf16 v[0:15], v[218:221], v[166:169], v[0:15]
	s_and_b64 vcc, s[8:9], vcc
	s_or_b64 s[6:7], s[6:7], vcc
	v_add_u32_e32 v211, s76, v243
	ds_read_b128 v[166:169], v199 offset:6752
	ds_read_b128 v[218:221], v199 offset:6784
	ds_read_b128 v[248:251], v199 offset:6816
	s_waitcnt lgkmcnt(3)
	v_mfma_f32_32x32x16_bf16 v[64:79], v[64:67], v[98:101], 0
	v_add_f32_e32 v82, v81, v82
	v_cvt_pk_bf16_f32 v163, v80, v81
	v_mfma_f32_32x32x16_bf16 v[64:79], v[182:185], v[102:105], v[64:79]
	v_exp_f32_e32 v80, v84
	v_exp_f32_e32 v81, v85
	v_add_f32_e32 v82, v80, v82
	v_add_f32_e32 v82, v81, v82
	v_cvt_pk_bf16_f32 v164, v80, v81
	v_mfma_f32_32x32x16_bf16 v[64:79], v[174:177], v[106:109], v[64:79]
	v_exp_f32_e32 v80, v86
	v_exp_f32_e32 v81, v87
	v_add_f32_e32 v82, v80, v82
	v_add_f32_e32 v174, v81, v82
	v_cvt_pk_bf16_f32 v165, v80, v81
	s_waitcnt lgkmcnt(0)
	v_mfma_f32_32x32x16_bf16 v[64:79], v[166:169], v[110:113], v[64:79]
	ds_read_b128 v[80:83], v211 offset:13312
	ds_read_b128 v[84:87], v211 offset:13344
	ds_read_b128 v[182:185], v211 offset:17920
	ds_read_b128 v[222:225], v211 offset:17952
	v_exp_f32_e32 v88, v88
	v_exp_f32_e32 v89, v89
	v_add_f32_e32 v166, v88, v174
	v_add_f32_e32 v166, v89, v166
	v_cvt_pk_bf16_f32 v174, v88, v89
	v_mfma_f32_32x32x16_bf16 v[64:79], v[218:221], v[114:117], v[64:79]
	v_exp_f32_e32 v88, v90
	v_exp_f32_e32 v89, v91
	v_add_f32_e32 v90, v88, v166
	v_add_f32_e32 v90, v89, v90
	v_cvt_pk_bf16_f32 v175, v88, v89
	v_mfma_f32_32x32x16_bf16 v[64:79], v[248:251], v[118:121], v[64:79]
	v_exp_f32_e32 v88, v92
	v_exp_f32_e32 v89, v93
	v_add_f32_e32 v90, v88, v90
	v_add_f32_e32 v90, v89, v90
	v_cvt_pk_bf16_f32 v176, v88, v89
	s_waitcnt lgkmcnt(0)
	v_mfma_f32_32x32x16_bf16 v[48:63], v[80:83], v[178:181], v[48:63]
	v_exp_f32_e32 v80, v94
	v_exp_f32_e32 v81, v95
	v_add_f32_e32 v82, v80, v90
	v_add_f32_e32 v247, v81, v82
	v_cvt_pk_bf16_f32 v177, v80, v81
	v_mfma_f32_32x32x16_bf16 v[32:47], v[182:185], v[178:181], v[32:47]
	ds_read_b128 v[80:83], v199 offset:6656
	ds_read_b128 v[182:185], v199 offset:6688
	ds_read_b128 v[178:181], v199 offset:6720
	v_cmp_nge_f32_e64 s[10:11], s48, v247
	v_cmp_gt_f32_e32 vcc, s49, v247
	v_mfma_f32_32x32x16_bf16 v[48:63], v[84:87], v[170:173], v[48:63]
	v_exp_f32_e32 v64, v64
	v_exp_f32_e32 v65, v65
	s_nop 0
	v_add_f32_e32 v84, v65, v64
	v_cvt_pk_bf16_f32 v166, v64, v65
	v_exp_f32_e32 v64, v66
	v_exp_f32_e32 v65, v67
	v_add_f32_e32 v66, v64, v84
	v_mfma_f32_32x32x16_bf16 v[32:47], v[222:225], v[170:173], v[32:47]
	s_and_b64 s[8:9], s[8:9], vcc
	s_or_b64 s[8:9], s[8:9], s[10:11]
	ds_read_b128 v[170:173], v199 offset:6752
	ds_read_b128 v[218:221], v199 offset:6784
	ds_read_b128 v[222:225], v199 offset:6816
	s_waitcnt lgkmcnt(3)
	v_mfma_f32_32x32x16_bf16 v[80:95], v[80:83], v[122:125], 0
	v_add_f32_e32 v66, v65, v66
	v_cvt_pk_bf16_f32 v167, v64, v65
	v_mfma_f32_32x32x16_bf16 v[80:95], v[182:185], v[126:129], v[80:95]
	v_exp_f32_e32 v64, v68
	v_exp_f32_e32 v65, v69
	v_add_f32_e32 v66, v64, v66
	v_add_f32_e32 v66, v65, v66
	v_cvt_pk_bf16_f32 v168, v64, v65
	v_mfma_f32_32x32x16_bf16 v[80:95], v[178:181], v[130:133], v[80:95]
	v_exp_f32_e32 v64, v70
	v_exp_f32_e32 v65, v71
	v_add_f32_e32 v66, v64, v66
	v_add_f32_e32 v178, v65, v66
	v_cvt_pk_bf16_f32 v169, v64, v65
	s_waitcnt lgkmcnt(0)
	v_mfma_f32_32x32x16_bf16 v[80:95], v[170:173], v[134:137], v[80:95]
	ds_read_b128 v[64:67], v211 offset:13312
	ds_read_b128 v[68:71], v211 offset:13344
	ds_read_b128 v[182:185], v211 offset:17920
	ds_read_b128 v[248:251], v211 offset:17952
	v_exp_f32_e32 v72, v72
	v_exp_f32_e32 v73, v73
	v_add_f32_e32 v170, v72, v178
	v_add_f32_e32 v170, v73, v170
	v_cvt_pk_bf16_f32 v178, v72, v73
	v_mfma_f32_32x32x16_bf16 v[80:95], v[218:221], v[154:157], v[80:95]
	v_exp_f32_e32 v72, v74
	v_exp_f32_e32 v73, v75
	v_add_f32_e32 v74, v72, v170
	v_add_f32_e32 v74, v73, v74
	v_cvt_pk_bf16_f32 v179, v72, v73
	v_mfma_f32_32x32x16_bf16 v[80:95], v[222:225], v[158:161], v[80:95]
	v_exp_f32_e32 v72, v76
	v_exp_f32_e32 v73, v77
	v_add_f32_e32 v74, v72, v74
	v_add_f32_e32 v74, v73, v74
	v_cvt_pk_bf16_f32 v180, v72, v73
	s_waitcnt lgkmcnt(0)
	v_mfma_f32_32x32x16_bf16 v[16:31], v[64:67], v[162:165], v[16:31]
	v_exp_f32_e32 v64, v78
	v_exp_f32_e32 v65, v79
	v_add_f32_e32 v66, v64, v74
	v_add_f32_e32 v210, v65, v66
	v_cvt_pk_bf16_f32 v181, v64, v65
	v_mfma_f32_32x32x16_bf16 v[0:15], v[182:185], v[162:165], v[0:15]
	v_add_u32_e32 v226, s78, v242
	ds_read_b128 v[64:67], v226 offset:22528
	ds_read_b128 v[170:173], v226 offset:22560
	ds_read_b128 v[182:185], v226 offset:22592
	v_cmp_nge_f32_e64 s[10:11], s48, v210
	v_mfma_f32_32x32x16_bf16 v[16:31], v[68:71], v[174:177], v[16:31]
	v_exp_f32_e32 v68, v80
	v_exp_f32_e32 v69, v81
	s_nop 0
	v_add_f32_e32 v70, v69, v68
	v_cvt_pk_bf16_f32 v162, v68, v69
	v_exp_f32_e32 v80, v82
	v_exp_f32_e32 v81, v83
	v_add_f32_e32 v82, v80, v70
	v_mfma_f32_32x32x16_bf16 v[0:15], v[248:251], v[174:177], v[0:15]
	ds_read_b128 v[174:177], v226 offset:22624
	ds_read_b128 v[218:221], v226 offset:22656
	ds_read_b128 v[222:225], v226 offset:22688
	s_waitcnt lgkmcnt(3)
	v_mfma_f32_32x32x16_bf16 v[64:79], v[64:67], v[98:101], 0
	v_add_f32_e32 v82, v81, v82
	v_cvt_pk_bf16_f32 v163, v80, v81
	v_mfma_f32_32x32x16_bf16 v[64:79], v[170:173], v[102:105], v[64:79]
	v_exp_f32_e32 v80, v84
	v_exp_f32_e32 v81, v85
	v_add_f32_e32 v82, v80, v82
	v_add_f32_e32 v82, v81, v82
	v_cvt_pk_bf16_f32 v164, v80, v81
	v_mfma_f32_32x32x16_bf16 v[64:79], v[182:185], v[106:109], v[64:79]
	v_exp_f32_e32 v80, v86
	v_exp_f32_e32 v81, v87
	v_add_f32_e32 v82, v80, v82
	v_add_f32_e32 v170, v81, v82
	v_cvt_pk_bf16_f32 v165, v80, v81
	s_waitcnt lgkmcnt(0)
	v_mfma_f32_32x32x16_bf16 v[64:79], v[174:177], v[110:113], v[64:79]
	ds_read_b128 v[80:83], v211 offset:13376
	ds_read_b128 v[84:87], v211 offset:13408
	ds_read_b128 v[182:185], v211 offset:17984
	ds_read_b128 v[248:251], v211 offset:18016
	v_exp_f32_e32 v88, v88
	v_exp_f32_e32 v89, v89
	v_add_f32_e32 v170, v88, v170
	v_add_f32_e32 v171, v89, v170
	v_cvt_pk_bf16_f32 v170, v88, v89
	v_mfma_f32_32x32x16_bf16 v[64:79], v[218:221], v[114:117], v[64:79]
	v_exp_f32_e32 v88, v90
	v_exp_f32_e32 v89, v91
	v_add_f32_e32 v90, v88, v171
	v_add_f32_e32 v90, v89, v90
	v_cvt_pk_bf16_f32 v171, v88, v89
	v_mfma_f32_32x32x16_bf16 v[64:79], v[222:225], v[118:121], v[64:79]
	v_exp_f32_e32 v88, v92
	v_exp_f32_e32 v89, v93
	v_add_f32_e32 v90, v88, v90
	v_add_f32_e32 v90, v89, v90
	v_cvt_pk_bf16_f32 v172, v88, v89
	s_waitcnt lgkmcnt(0)
	v_mfma_f32_32x32x16_bf16 v[48:63], v[80:83], v[166:169], v[48:63]
	v_exp_f32_e32 v80, v94
	v_exp_f32_e32 v81, v95
	v_add_f32_e32 v82, v80, v90
	v_add_f32_e32 v211, v81, v82
	v_cvt_pk_bf16_f32 v173, v80, v81
	v_mfma_f32_32x32x16_bf16 v[32:47], v[182:185], v[166:169], v[32:47]
	ds_read_b128 v[80:83], v226 offset:22528
	ds_read_b128 v[182:185], v226 offset:22560
	ds_read_b128 v[174:177], v226 offset:22592
	v_cmp_nge_f32_e64 s[12:13], s48, v211
	v_mfma_f32_32x32x16_bf16 v[48:63], v[84:87], v[178:181], v[48:63]
	s_barrier
	s_waitcnt lgkmcnt(0)
	v_mfma_f32_32x32x16_bf16 v[32:47], v[248:251], v[178:181], v[32:47]
	s_cmpk_gt_u32 s61, 0xfc
	s_cbranch_scc1 .LBB0_933
	s_add_i32 s24, s79, 0
	v_add_u32_e32 v84, s24, v238
	v_add_u32_e32 v85, s24, v245
	v_add_u32_e32 v86, s24, v198
	s_waitcnt vmcnt(0)
	ds_write_b128 v84, v[150:153]
	ds_write_b64 v85, v[190:191] offset:128
	ds_write_b128 v86, v[138:141] offset:13312

.LBB0_935:
	s_or_b64 s[6:7], s[8:9], s[6:7]
	v_add_f32_e32 v84, v204, v246
	v_add_f32_e32 v85, v205, v247
	s_or_b64 s[6:7], s[6:7], s[10:11]
	s_or_b64 s[6:7], s[6:7], s[12:13]
	v_add_f32_e32 v178, v84, v210
	v_add_f32_e32 v179, v85, v211
	s_xor_b32 s10, s77, 2
	v_add_u32_e32 v222, s78, v244
	v_exp_f32_e32 v64, v64
	v_exp_f32_e32 v65, v65
	s_nop 0
	v_add_f32_e32 v84, v65, v64
	v_cvt_pk_bf16_f32 v166, v64, v65
	v_exp_f32_e32 v64, v66
	ds_read_b128 v[204:207], v199 offset:22624
	ds_read_b128 v[208:211], v199 offset:22656
	ds_read_b128 v[218:221], v199 offset:22688
	v_exp_f32_e32 v65, v67
	v_add_f32_e32 v66, v64, v84
	v_mfma_f32_32x32x16_bf16 v[80:95], v[80:83], v[122:125], 0
	v_add_f32_e32 v66, v65, v66
	v_cvt_pk_bf16_f32 v167, v64, v65
	v_mfma_f32_32x32x16_bf16 v[80:95], v[182:185], v[126:129], v[80:95]
	v_exp_f32_e32 v64, v68
	v_exp_f32_e32 v65, v69
	v_add_f32_e32 v66, v64, v66
	v_add_f32_e32 v66, v65, v66
	v_cvt_pk_bf16_f32 v168, v64, v65
	v_mfma_f32_32x32x16_bf16 v[80:95], v[174:177], v[130:133], v[80:95]
	v_exp_f32_e32 v64, v70
	v_exp_f32_e32 v65, v71
	v_add_f32_e32 v66, v64, v66
	v_add_f32_e32 v174, v65, v66
	v_cvt_pk_bf16_f32 v169, v64, v65
	s_waitcnt lgkmcnt(0)
	v_mfma_f32_32x32x16_bf16 v[80:95], v[204:207], v[134:137], v[80:95]
	ds_read_b128 v[64:67], v222 offset:13376
	ds_read_b128 v[68:71], v222 offset:13408
	ds_read_b128 v[180:183], v222 offset:17984
	ds_read_b128 v[222:225], v222 offset:18016
	v_exp_f32_e32 v72, v72
	v_exp_f32_e32 v73, v73
	v_add_f32_e32 v174, v72, v174
	v_add_f32_e32 v175, v73, v174
	v_cvt_pk_bf16_f32 v174, v72, v73
	v_mfma_f32_32x32x16_bf16 v[80:95], v[208:211], v[154:157], v[80:95]
	v_exp_f32_e32 v72, v74
	v_exp_f32_e32 v73, v75
	v_add_f32_e32 v74, v72, v175
	v_add_f32_e32 v74, v73, v74
	v_cvt_pk_bf16_f32 v175, v72, v73
	v_mfma_f32_32x32x16_bf16 v[80:95], v[218:221], v[158:161], v[80:95]
	v_exp_f32_e32 v72, v76
	v_exp_f32_e32 v73, v77
	v_add_f32_e32 v74, v72, v74
	v_add_f32_e32 v74, v73, v74
	v_cvt_pk_bf16_f32 v176, v72, v73
	s_waitcnt lgkmcnt(0)
	v_mfma_f32_32x32x16_bf16 v[16:31], v[64:67], v[162:165], v[16:31]
	v_exp_f32_e32 v64, v78
	v_exp_f32_e32 v65, v79
	v_add_f32_e32 v66, v64, v74
	v_add_f32_e32 v204, v65, v66
	v_cvt_pk_bf16_f32 v177, v64, v65
	v_mfma_f32_32x32x16_bf16 v[0:15], v[180:183], v[162:165], v[0:15]
	ds_read_b128 v[64:67], v199 offset:29184
	ds_read_b128 v[180:183], v199 offset:29216
	ds_read_b128 v[208:211], v199 offset:29248
	v_cmp_nge_f32_e32 vcc, s48, v204
	v_mfma_f32_32x32x16_bf16 v[16:31], v[68:71], v[170:173], v[16:31]
	v_mfma_f32_32x32x16_bf16 v[0:15], v[222:225], v[170:173], v[0:15]
	v_mad_u32_u24 v68, v187, s69, v186
	v_add_u32_e32 v206, s76, v68
	v_exp_f32_e32 v68, v80
	v_exp_f32_e32 v69, v81
	s_nop 0
	v_add_f32_e32 v70, v69, v68
	v_cvt_pk_bf16_f32 v162, v68, v69
	v_exp_f32_e32 v80, v82
	ds_read_b128 v[170:173], v199 offset:29280
	ds_read_b128 v[218:221], v199 offset:29312
	ds_read_b128 v[222:225], v199 offset:29344
	v_exp_f32_e32 v81, v83
	v_add_f32_e32 v82, v80, v70
	s_waitcnt lgkmcnt(3)
	v_mfma_f32_32x32x16_bf16 v[64:79], v[64:67], v[98:101], 0
	v_add_f32_e32 v82, v81, v82
	v_cvt_pk_bf16_f32 v163, v80, v81
	v_mfma_f32_32x32x16_bf16 v[64:79], v[180:183], v[102:105], v[64:79]
	v_exp_f32_e32 v80, v84
	v_exp_f32_e32 v81, v85
	v_add_f32_e32 v82, v80, v82
	v_add_f32_e32 v82, v81, v82
	v_cvt_pk_bf16_f32 v164, v80, v81
	v_mfma_f32_32x32x16_bf16 v[64:79], v[208:211], v[106:109], v[64:79]
	v_exp_f32_e32 v80, v86
	v_exp_f32_e32 v81, v87
	v_add_f32_e32 v82, v80, v82
	v_add_f32_e32 v184, v81, v82
	v_cvt_pk_bf16_f32 v165, v80, v81
	s_waitcnt lgkmcnt(0)
	v_mfma_f32_32x32x16_bf16 v[64:79], v[170:173], v[110:113], v[64:79]
	ds_read_b128 v[80:83], v206 offset:35840
	ds_read_b128 v[84:87], v206 offset:35872
	ds_read_b128 v[180:183], v206 offset:40448
	ds_read_b128 v[208:211], v206 offset:40480
	v_exp_f32_e32 v88, v88
	v_exp_f32_e32 v89, v89
	v_add_f32_e32 v170, v88, v184
	v_add_f32_e32 v171, v89, v170
	v_cvt_pk_bf16_f32 v170, v88, v89
	v_mfma_f32_32x32x16_bf16 v[64:79], v[218:221], v[114:117], v[64:79]
	v_exp_f32_e32 v88, v90
	v_exp_f32_e32 v89, v91
	v_add_f32_e32 v90, v88, v171
	v_add_f32_e32 v90, v89, v90
	v_cvt_pk_bf16_f32 v171, v88, v89
	v_mfma_f32_32x32x16_bf16 v[64:79], v[222:225], v[118:121], v[64:79]
	v_exp_f32_e32 v88, v92
	v_exp_f32_e32 v89, v93
	v_add_f32_e32 v90, v88, v90
	v_add_f32_e32 v90, v89, v90
	v_cvt_pk_bf16_f32 v172, v88, v89
	s_waitcnt lgkmcnt(0)
	v_mfma_f32_32x32x16_bf16 v[48:63], v[80:83], v[166:169], v[48:63]
	v_exp_f32_e32 v80, v94
	v_exp_f32_e32 v81, v95
	v_add_f32_e32 v82, v80, v90
	v_add_f32_e32 v205, v81, v82
	v_cvt_pk_bf16_f32 v173, v80, v81
	v_mfma_f32_32x32x16_bf16 v[32:47], v[180:183], v[166:169], v[32:47]
	ds_read_b128 v[80:83], v199 offset:29184
	ds_read_b128 v[166:169], v199 offset:29216
	ds_read_b128 v[182:185], v199 offset:29248
	s_or_b64 s[8:9], s[6:7], vcc
	v_cmp_nge_f32_e32 vcc, s48, v205
	v_add_f32_e32 v204, v178, v204
	v_add_f32_e32 v205, v179, v205
	v_mfma_f32_32x32x16_bf16 v[48:63], v[84:87], v[174:177], v[48:63]
	v_exp_f32_e32 v64, v64
	v_exp_f32_e32 v65, v65
	s_nop 0
	v_add_f32_e32 v84, v65, v64
	v_cvt_pk_bf16_f32 v178, v64, v65
	v_exp_f32_e32 v64, v66
	v_exp_f32_e32 v65, v67
	v_add_f32_e32 v66, v64, v84
	v_mfma_f32_32x32x16_bf16 v[32:47], v[208:211], v[174:177], v[32:47]
	ds_read_b128 v[174:177], v199 offset:29280
	ds_read_b128 v[208:211], v199 offset:29312
	ds_read_b128 v[218:221], v199 offset:29344
	s_waitcnt lgkmcnt(3)
; template <int MODE, bool FAST> __device__ __forceinline__ bool attn_unit(LAS unsigned char* lds, const AttU& U, const int wv) {
;     ...
;         for (int t2 = U.kt0; t2 < U.kt1; t2 += 2) { ATT_TILE(t2, 4, rk, rr, rv); ATT_TILE(t2 + 1, 4, rk2, rr2, rv2); }
	v_mfma_f32_32x32x16_bf16 v[80:95], v[80:83], v[122:125], 0
	v_add_f32_e32 v66, v65, v66
	v_cvt_pk_bf16_f32 v179, v64, v65
	v_mfma_f32_32x32x16_bf16 v[80:95], v[166:169], v[126:129], v[80:95]
	v_exp_f32_e32 v64, v68
	v_exp_f32_e32 v65, v69
	v_add_f32_e32 v66, v64, v66
	v_add_f32_e32 v66, v65, v66
	v_cvt_pk_bf16_f32 v180, v64, v65
	v_mfma_f32_32x32x16_bf16 v[80:95], v[182:185], v[130:133], v[80:95]
	v_exp_f32_e32 v64, v70
	v_exp_f32_e32 v65, v71
	v_add_f32_e32 v66, v64, v66
	v_add_f32_e32 v182, v65, v66
	v_cvt_pk_bf16_f32 v181, v64, v65
	s_waitcnt lgkmcnt(0)
	v_mfma_f32_32x32x16_bf16 v[80:95], v[174:177], v[134:137], v[80:95]
	ds_read_b128 v[64:67], v206 offset:35840
	ds_read_b128 v[68:71], v206 offset:35872
	ds_read_b128 v[166:169], v206 offset:40448
	ds_read_b128 v[222:225], v206 offset:40480
	v_exp_f32_e32 v72, v72
	v_exp_f32_e32 v73, v73
	v_add_f32_e32 v174, v72, v182
	v_add_f32_e32 v174, v73, v174
	v_cvt_pk_bf16_f32 v182, v72, v73
	v_mfma_f32_32x32x16_bf16 v[80:95], v[208:211], v[154:157], v[80:95]
	v_exp_f32_e32 v72, v74
	v_exp_f32_e32 v73, v75
	v_add_f32_e32 v74, v72, v174
	v_add_f32_e32 v74, v73, v74
	v_cvt_pk_bf16_f32 v183, v72, v73
	v_mfma_f32_32x32x16_bf16 v[80:95], v[218:221], v[158:161], v[80:95]
	v_exp_f32_e32 v72, v76
	v_exp_f32_e32 v73, v77
	v_add_f32_e32 v74, v72, v74
	v_add_f32_e32 v74, v73, v74
	v_cvt_pk_bf16_f32 v184, v72, v73
	s_waitcnt lgkmcnt(0)
	v_mfma_f32_32x32x16_bf16 v[16:31], v[64:67], v[162:165], v[16:31]
	v_exp_f32_e32 v64, v78
	v_exp_f32_e32 v65, v79
	v_add_f32_e32 v66, v64, v74
	v_add_f32_e32 v226, v65, v66
	v_cvt_pk_bf16_f32 v185, v64, v65
	v_mfma_f32_32x32x16_bf16 v[0:15], v[166:169], v[162:165], v[0:15]
	s_mulk_i32 s10, 0x5800
	v_add_u32_e32 v199, s10, v242
	ds_read_b128 v[64:67], v199
	ds_read_b128 v[164:167], v199 offset:32
	ds_read_b128 v[174:177], v199 offset:64
	v_cmp_nge_f32_e64 s[6:7], s48, v226
	v_mfma_f32_32x32x16_bf16 v[16:31], v[68:71], v[170:173], v[16:31]
	v_exp_f32_e32 v68, v80
	v_exp_f32_e32 v69, v81
	s_nop 0
	v_add_f32_e32 v70, v69, v68
	v_cvt_pk_bf16_f32 v162, v68, v69
	v_exp_f32_e32 v80, v82
	v_exp_f32_e32 v81, v83
	v_add_f32_e32 v82, v80, v70
	v_mfma_f32_32x32x16_bf16 v[0:15], v[222:225], v[170:173], v[0:15]
	s_or_b64 s[8:9], s[8:9], vcc
	ds_read_b128 v[168:171], v199 offset:96
	ds_read_b128 v[208:211], v199 offset:128
	ds_read_b128 v[218:221], v199 offset:160
	s_waitcnt lgkmcnt(3)
	v_mfma_f32_32x32x16_bf16 v[64:79], v[64:67], v[98:101], 0
	v_add_f32_e32 v82, v81, v82
	v_cvt_pk_bf16_f32 v163, v80, v81
	v_mfma_f32_32x32x16_bf16 v[64:79], v[164:167], v[102:105], v[64:79]
	v_exp_f32_e32 v80, v84
	v_exp_f32_e32 v81, v85
	v_add_f32_e32 v82, v80, v82
	v_add_f32_e32 v82, v81, v82
	v_cvt_pk_bf16_f32 v164, v80, v81
	v_mfma_f32_32x32x16_bf16 v[64:79], v[174:177], v[106:109], v[64:79]
	v_exp_f32_e32 v80, v86
	v_exp_f32_e32 v81, v87
	v_add_f32_e32 v82, v80, v82
	v_add_f32_e32 v166, v81, v82
	v_cvt_pk_bf16_f32 v165, v80, v81
	s_waitcnt lgkmcnt(0)
	v_mfma_f32_32x32x16_bf16 v[64:79], v[168:171], v[110:113], v[64:79]
	ds_read_b128 v[80:83], v206 offset:35904
	ds_read_b128 v[84:87], v206 offset:35936
	ds_read_b128 v[222:225], v206 offset:40512
	ds_read_b128 v[246:249], v206 offset:40544
	v_exp_f32_e32 v88, v88
	v_exp_f32_e32 v89, v89
	v_add_f32_e32 v166, v88, v166
	v_add_f32_e32 v167, v89, v166
	v_cvt_pk_bf16_f32 v166, v88, v89
	v_mfma_f32_32x32x16_bf16 v[64:79], v[208:211], v[114:117], v[64:79]
	v_exp_f32_e32 v88, v90
	v_exp_f32_e32 v89, v91
	v_add_f32_e32 v90, v88, v167
	v_add_f32_e32 v90, v89, v90
	v_cvt_pk_bf16_f32 v167, v88, v89
	v_mfma_f32_32x32x16_bf16 v[64:79], v[218:221], v[118:121], v[64:79]
	v_exp_f32_e32 v88, v92
	v_exp_f32_e32 v89, v93
	v_add_f32_e32 v90, v88, v90
	v_add_f32_e32 v90, v89, v90
	v_cvt_pk_bf16_f32 v168, v88, v89
	s_waitcnt lgkmcnt(0)
	v_mfma_f32_32x32x16_bf16 v[48:63], v[80:83], v[178:181], v[48:63]
	v_exp_f32_e32 v80, v94
	v_exp_f32_e32 v81, v95
	v_add_f32_e32 v82, v80, v90
	v_add_f32_e32 v227, v81, v82
	v_cvt_pk_bf16_f32 v169, v80, v81
	v_mfma_f32_32x32x16_bf16 v[32:47], v[222:225], v[178:181], v[32:47]
	ds_read_b128 v[80:83], v199
	ds_read_b128 v[174:177], v199 offset:32
	ds_read_b128 v[170:173], v199 offset:64
	s_or_b64 s[6:7], s[8:9], s[6:7]
	v_cmp_nge_f32_e32 vcc, s48, v227
	s_or_b64 s[6:7], s[6:7], vcc
	s_cmp_lg_u64 s[6:7], 0
	s_cselect_b64 s[6:7], -1, 0
	s_or_b64 s[42:43], s[42:43], s[6:7]
	v_mfma_f32_32x32x16_bf16 v[48:63], v[84:87], v[182:185], v[48:63]
	v_add_f32_e32 v204, v204, v226
	v_add_f32_e32 v205, v205, v227
	s_barrier
	s_waitcnt lgkmcnt(0)
	v_mfma_f32_32x32x16_bf16 v[32:47], v[246:249], v[182:185], v[32:47]
	s_add_u32 s40, s40, 0x40000
	s_mov_b64 s[6:7], 0x2000
	s_addc_u32 s41, s41, 0
	v_lshl_add_u64 v[202:203], v[202:203], 0, s[6:7]
	s_and_b64 vcc, exec, s[44:45]
	s_cbranch_vccnz .LBB0_937
	s_mov_b32 s61, s30
	s_branch .LBB0_923
